# all 7 weight-copy loops: waits relocated so the next item's loads stay in flight during transpose/stores
# speedup vs baseline: 1.0019x; 1.0019x over previous
;     ...
;     TrItem tc, tn; f32x4 vc[16], vn[16];
;     int it = it0 + gw;
;     if (it < it1) { TR_DESCRIBE(it, tc); tr_load(tc, vc, lane); }
;     for (; it < it1; it += NGW) {
;         const bool more = it + NGW < it1;
;         if (more) { TR_DESCRIBE(it + NGW, tn); tr_load(tn, vn, lane); }
.LBB0_57:
	s_waitcnt vmcnt(0)
	s_add_i32 s34, s34, s33
	s_cmpk_lt_i32 s34, 0x2c20
	s_cselect_b64 s[26:27], -1, 0
	s_cmpk_gt_i32 s34, 0x2c1f
	s_cselect_b64 s[24:25], -1, 0
	s_and_b64 vcc, exec, s[24:25]
	s_cbranch_vccnz .LBB0_81
	s_cmpk_gt_i32 s34, 0x15ff
	s_cbranch_scc0 .LBB0_62
	s_cmpk_gt_u32 s34, 0x20ff
	s_cbranch_scc0 .LBB0_99
	s_add_i32 s15, s34, 0xdf00
	s_and_b32 s20, s15, 0xffff
	s_mulk_i32 s20, 0x702f
	s_lshr_b32 s20, s20, 16
	s_sub_i32 s21, s15, s20
	s_bfe_u32 s21, s21, 0xf0001
	s_add_i32 s21, s21, s20
	s_bfe_u32 s20, s21, 0xa0006
	s_mulk_i32 s20, 0x59
	s_sub_i32 s15, s15, s20
	s_lshl_b32 s15, s15, 6
	s_and_b32 s20, s15, 0xffc0
	s_and_b32 s41, s21, 0xffc0
	s_waitcnt lgkmcnt(0)
	s_mov_b64 s[28:29], s[6:7]
	s_cbranch_execz .LBB0_100
	s_movk_i32 s43, 0x1620
	s_movk_i32 s42, 0x800
	s_mov_b64 s[22:23], s[12:13]
	s_mov_b32 s44, s20
	s_cbranch_execz .LBB0_63
	s_branch .LBB0_64

; #define LAS __attribute__((address_space(3)))
; __device__ __forceinline__ unsigned pk2(float lo, float hi) { return cvtpk(lo, hi); }
; __device__ __forceinline__ void tr_finish(const TrItem& t, const f32x4 (&v)[16], LAS float* scr, int lane) {
;     const int c4 = 4 * (lane & 15), kq = lane >> 4;
; #pragma unroll
;     for (int i = 0; i < 16; ++i) { LAS float* d = scr + (4 * i + kq) * 65 + c4; d[0] = v[i].x; d[1] = v[i].y; d[2] = v[i].z; d[3] = v[i].w; }
;     asm volatile("s_waitcnt lgkmcnt(0)" ::: "memory");
;     const int c = lane & 7;
; #pragma unroll
;     for (int j = 0; j < 8; ++j) { const int n = (lane >> 3) + 8 * j; const LAS float* s = scr + (8 * c) * 65 + n;
;         v4u o; o.x = pk2(s[0 * 65], s[1 * 65]); o.y = pk2(s[2 * 65], s[3 * 65]); o.z = pk2(s[4 * 65], s[5 * 65]); o.w = pk2(s[6 * 65], s[7 * 65]);
;         if (t.n0 + n < t.N) *(v4u*)(t.WT + (size_t)(t.drow0 + n) * t.K + t.k0 + 8 * c) = o; }
;     asm volatile("s_waitcnt lgkmcnt(0)" ::: "memory");
.LBB0_81:
	v_add_u32_e32 v67, 0x410, v164
	ds_write2_b32 v164, v6, v7 offset1:1
	ds_write2_b32 v164, v8, v9 offset0:2 offset1:3
	ds_write2_b32 v67, v10, v11 offset1:1
	v_add_u32_e32 v67, 0x418, v164
	ds_write2_b32 v67, v12, v13 offset1:1
	v_add_u32_e32 v67, 0x820, v164
	ds_write2_b32 v67, v14, v15 offset1:1
	v_add_u32_e32 v67, 0x828, v164
	ds_write2_b32 v67, v16, v17 offset1:1
	v_add_u32_e32 v67, 0xc30, v164
	ds_write2_b32 v67, v2, v3 offset1:1
	v_add_u32_e32 v67, 0xc38, v164
	ds_write2_b32 v67, v4, v5 offset1:1
	v_add_u32_e32 v67, 0x1040, v164
	ds_write2_b32 v67, v22, v23 offset1:1
	v_add_u32_e32 v67, 0x1048, v164
	ds_write2_b32 v67, v24, v25 offset1:1
	v_add_u32_e32 v67, 0x1450, v164
	ds_write2_b32 v67, v26, v27 offset1:1
	v_add_u32_e32 v67, 0x1458, v164
	ds_write2_b32 v67, v28, v29 offset1:1
	v_add_u32_e32 v67, 0x1860, v164
	ds_write2_b32 v67, v30, v31 offset1:1
	v_add_u32_e32 v67, 0x1868, v164
	ds_write2_b32 v67, v32, v33 offset1:1
	v_add_u32_e32 v67, 0x1c70, v164
	ds_write2_b32 v67, v18, v19 offset1:1
	v_add_u32_e32 v67, 0x1c78, v164
	ds_write2_b32 v67, v20, v21 offset1:1
	v_add_u32_e32 v67, 0x2080, v164
	ds_write2_b32 v67, v38, v39 offset1:1
	v_add_u32_e32 v67, 0x2088, v164
	ds_write2_b32 v67, v40, v41 offset1:1
	v_add_u32_e32 v67, 0x2490, v164
	ds_write2_b32 v67, v42, v43 offset1:1
	v_add_u32_e32 v67, 0x2498, v164
	ds_write2_b32 v67, v44, v45 offset1:1
	v_add_u32_e32 v67, 0x28a0, v164
	ds_write2_b32 v67, v46, v47 offset1:1
	v_add_u32_e32 v67, 0x28a8, v164
	ds_write2_b32 v67, v48, v49 offset1:1
	v_add_u32_e32 v67, 0x2cb0, v164
	ds_write2_b32 v67, v34, v35 offset1:1
	v_add_u32_e32 v67, 0x2cb8, v164
	ds_write2_b32 v67, v36, v37 offset1:1
	v_add_u32_e32 v67, 0x30c0, v164
	ds_write2_b32 v67, v54, v55 offset1:1
	v_add_u32_e32 v67, 0x30c8, v164
	ds_write2_b32 v67, v56, v57 offset1:1
	v_add_u32_e32 v67, 0x34d0, v164
	ds_write2_b32 v67, v58, v59 offset1:1
	v_add_u32_e32 v67, 0x34d8, v164
	ds_write2_b32 v67, v60, v61 offset1:1
	v_add_u32_e32 v67, 0x38e0, v164
	ds_write2_b32 v67, v50, v51 offset1:1
	v_add_u32_e32 v67, 0x38e8, v164
	ds_write2_b32 v67, v52, v53 offset1:1
	v_add_u32_e32 v67, 0x3cf0, v164
	ds_write2_b32 v67, v62, v63 offset1:1
	v_add_u32_e32 v67, 0x3cf8, v164
	ds_write2_b32 v67, v64, v65 offset1:1
	s_waitcnt lgkmcnt(0)
	ds_read2_b32 v[68:69], v156 offset1:65
	ds_read2_b32 v[136:137], v156 offset0:130 offset1:195
	v_add_u32_e32 v67, 0x400, v156
	ds_read2_b32 v[166:167], v67 offset0:4 offset1:69
	ds_read2_b32 v[168:169], v67 offset0:134 offset1:199
	s_waitcnt lgkmcnt(0)
	v_cvt_pk_bf16_f32 v134, v68, v69
	v_add_u32_e32 v68, s18, v155
	v_cmp_gt_i32_e32 vcc, s37, v68
	v_lshlrev_b32_e32 v68, 1, v140
	v_cvt_pk_bf16_f32 v135, v136, v137
	v_cvt_pk_bf16_f32 v136, v166, v167
	v_cvt_pk_bf16_f32 v137, v168, v169
	s_and_saveexec_b64 s[28:29], vcc
	s_cbranch_execz .LBB0_83
	v_add_u32_e32 v69, s35, v155
	v_mad_i64_i32 v[166:167], s[30:31], v69, s36, 0
	v_lshl_add_u64 v[166:167], v[166:167], 1, s[16:17]
	s_ashr_i32 s15, s14, 31
	v_lshl_add_u64 v[166:167], s[14:15], 1, v[166:167]
	v_mov_b32_e32 v69, v66
	v_lshl_add_u64 v[166:167], v[166:167], 0, v[68:69]
	global_store_dwordx4 v[166:167], v[134:137], off

;     ...
;     for (; it < it1; it += NGW) {
;         const bool more = it + NGW < it1;
;         if (more) { TR_DESCRIBE(it + NGW, tn); tr_load(tn, vn, lane); }
;         tr_finish(tc, vc, scr, lane);
;         if (more) { tc = tn;
; #pragma unroll
;             for (int i = 0; i < 16; ++i) vc[i] = vn[i]; }
.LBB0_97:
	s_or_b64 exec, exec, s[28:29]
	s_waitcnt lgkmcnt(0)
	s_andn2_b64 vcc, exec, s[26:27]
	s_cbranch_vccnz .LBB0_56
	s_waitcnt vmcnt(0)
	v_mov_b64_e32 v[62:63], v[130:131]
	v_mov_b64_e32 v[50:51], v[126:127]
	v_mov_b64_e32 v[58:59], v[118:119]
	v_mov_b64_e32 v[54:55], v[122:123]
	v_mov_b64_e32 v[34:35], v[110:111]
	v_mov_b64_e32 v[46:47], v[114:115]
	v_mov_b64_e32 v[42:43], v[102:103]
	v_mov_b64_e32 v[38:39], v[106:107]
	v_mov_b64_e32 v[18:19], v[94:95]
	v_mov_b64_e32 v[30:31], v[98:99]
	v_mov_b64_e32 v[26:27], v[86:87]
	v_mov_b64_e32 v[22:23], v[90:91]
	v_mov_b64_e32 v[2:3], v[78:79]
	v_mov_b64_e32 v[14:15], v[82:83]
	v_mov_b64_e32 v[10:11], v[70:71]
	v_mov_b64_e32 v[6:7], v[74:75]
	v_mov_b64_e32 v[64:65], v[132:133]
	v_mov_b64_e32 v[52:53], v[128:129]
	v_mov_b64_e32 v[60:61], v[120:121]
	v_mov_b64_e32 v[56:57], v[124:125]
	v_mov_b64_e32 v[36:37], v[112:113]
	v_mov_b64_e32 v[48:49], v[116:117]
	v_mov_b64_e32 v[44:45], v[104:105]
	v_mov_b64_e32 v[40:41], v[108:109]
	v_mov_b64_e32 v[20:21], v[96:97]
	v_mov_b64_e32 v[32:33], v[100:101]
	v_mov_b64_e32 v[28:29], v[88:89]
	v_mov_b64_e32 v[24:25], v[92:93]
	v_mov_b64_e32 v[4:5], v[80:81]
	v_mov_b64_e32 v[16:17], v[84:85]
	v_mov_b64_e32 v[12:13], v[72:73]
	v_mov_b64_e32 v[8:9], v[76:77]
	s_mov_b32 s14, s41
	s_mov_b32 s35, s44
	s_mov_b32 s37, s43
	s_mov_b32 s36, s42
	s_mov_b64 s[16:17], s[22:23]
	s_mov_b32 s18, s20
	s_branch .LBB0_56

; #define LAS __attribute__((address_space(3)))
; __device__ __forceinline__ unsigned pk2(float lo, float hi) { return cvtpk(lo, hi); }
; __device__ __forceinline__ void tr_finish(const TrItem& t, const f32x4 (&v)[16], LAS float* scr, int lane) {
;     const int c4 = 4 * (lane & 15), kq = lane >> 4;
; #pragma unroll
;     for (int i = 0; i < 16; ++i) { LAS float* d = scr + (4 * i + kq) * 65 + c4; d[0] = v[i].x; d[1] = v[i].y; d[2] = v[i].z; d[3] = v[i].w; }
;     asm volatile("s_waitcnt lgkmcnt(0)" ::: "memory");
;     const int c = lane & 7;
; #pragma unroll
;     for (int j = 0; j < 8; ++j) { const int n = (lane >> 3) + 8 * j; const LAS float* s = scr + (8 * c) * 65 + n;
;         v4u o; o.x = pk2(s[0 * 65], s[1 * 65]); o.y = pk2(s[2 * 65], s[3 * 65]); o.z = pk2(s[4 * 65], s[5 * 65]); o.w = pk2(s[6 * 65], s[7 * 65]);
;         if (t.n0 + n < t.N) *(v4u*)(t.WT + (size_t)(t.drow0 + n) * t.K + t.k0 + 8 * c) = o; }
;     asm volatile("s_waitcnt lgkmcnt(0)" ::: "memory");
;     ...
;         if (more) { tc = tn;
; #pragma unroll
;             for (int i = 0; i < 16; ++i) vc[i] = vn[i]; }
.LBB0_1192:
	v_add_u32_e32 v2, 0x410, v149
	ds_write2_b32 v149, v30, v31 offset1:1
	ds_write2_b32 v149, v32, v33 offset0:2 offset1:3
	ds_write2_b32 v2, v46, v47 offset1:1
	v_add_u32_e32 v2, 0x418, v149
	ds_write2_b32 v2, v48, v49 offset1:1
	v_add_u32_e32 v2, 0x820, v149
	ds_write2_b32 v2, v42, v43 offset1:1
	v_add_u32_e32 v2, 0x828, v149
	ds_write2_b32 v2, v44, v45 offset1:1
	v_add_u32_e32 v2, 0xc30, v149
	ds_write2_b32 v2, v54, v55 offset1:1
	v_add_u32_e32 v2, 0xc38, v149
	ds_write2_b32 v2, v56, v57 offset1:1
	v_add_u32_e32 v2, 0x1040, v149
	ds_write2_b32 v2, v50, v51 offset1:1
	v_add_u32_e32 v2, 0x1048, v149
	ds_write2_b32 v2, v52, v53 offset1:1
	v_add_u32_e32 v2, 0x1450, v149
	ds_write2_b32 v2, v62, v63 offset1:1
	v_add_u32_e32 v2, 0x1458, v149
	ds_write2_b32 v2, v64, v65 offset1:1
	v_add_u32_e32 v2, 0x1860, v149
	ds_write2_b32 v2, v58, v59 offset1:1
	v_add_u32_e32 v2, 0x1868, v149
	ds_write2_b32 v2, v60, v61 offset1:1
	v_add_u32_e32 v2, 0x1c70, v149
	ds_write2_b32 v2, v70, v71 offset1:1
	v_add_u32_e32 v2, 0x1c78, v149
	ds_write2_b32 v2, v72, v73 offset1:1
	v_add_u32_e32 v2, 0x2080, v149
	ds_write2_b32 v2, v66, v67 offset1:1
	v_add_u32_e32 v2, 0x2088, v149
	ds_write2_b32 v2, v68, v69 offset1:1
	v_add_u32_e32 v2, 0x2490, v149
	ds_write2_b32 v2, v78, v79 offset1:1
	v_add_u32_e32 v2, 0x2498, v149
	ds_write2_b32 v2, v80, v81 offset1:1
	v_add_u32_e32 v2, 0x28a0, v149
	ds_write2_b32 v2, v74, v75 offset1:1
	v_add_u32_e32 v2, 0x28a8, v149
	ds_write2_b32 v2, v76, v77 offset1:1
	v_add_u32_e32 v2, 0x2cb0, v149
	ds_write2_b32 v2, v86, v87 offset1:1
	v_add_u32_e32 v2, 0x2cb8, v149
	ds_write2_b32 v2, v88, v89 offset1:1
	v_add_u32_e32 v2, 0x30c0, v149
	ds_write2_b32 v2, v82, v83 offset1:1
	v_add_u32_e32 v2, 0x30c8, v149
	ds_write2_b32 v2, v84, v85 offset1:1
	v_add_u32_e32 v2, 0x34d0, v149
	ds_write2_b32 v2, v98, v99 offset1:1
	v_add_u32_e32 v2, 0x34d8, v149
	ds_write2_b32 v2, v100, v101 offset1:1
	v_add_u32_e32 v2, 0x38e0, v149
	ds_write2_b32 v2, v110, v111 offset1:1
	v_add_u32_e32 v2, 0x38e8, v149
	ds_write2_b32 v2, v112, v113 offset1:1
	v_add_u32_e32 v2, 0x3cf0, v149
	ds_write2_b32 v2, v114, v115 offset1:1
	v_add_u32_e32 v2, 0x3cf8, v149
	ds_write2_b32 v2, v116, v117 offset1:1
	s_waitcnt lgkmcnt(0)
	v_add_u32_e32 v2, 0x400, v141
	v_add_u32_e32 v56, s13, v140
	ds_read2_b32 v[4:5], v141 offset0:65 offset1:73
	ds_read2_b32 v[42:43], v141 offset1:8
	ds_read2_b32 v[44:45], v141 offset0:130 offset1:138
	ds_read2_b32 v[46:47], v141 offset0:195 offset1:203
	ds_read2_b32 v[48:49], v2 offset0:4 offset1:12
	ds_read2_b32 v[50:51], v2 offset0:69 offset1:77
	ds_read2_b32 v[52:53], v2 offset0:134 offset1:142
	ds_read2_b32 v[54:55], v2 offset0:199 offset1:207
	v_ashrrev_i32_e32 v57, 31, v56
	v_lshlrev_b64 v[56:57], 12, v[56:57]
	s_ashr_i32 s5, s4, 31
	v_lshl_add_u64 v[56:57], s[2:3], 0, v[56:57]
	s_lshl_b64 s[4:5], s[4:5], 1
	v_lshl_add_u64 v[56:57], v[56:57], 0, s[4:5]
	v_mov_b32_e32 v137, v3
	s_waitcnt lgkmcnt(6)
	v_cvt_pk_bf16_f32 v30, v42, v4
	v_lshl_add_u64 v[56:57], v[56:57], 0, v[136:137]
	v_add_u32_e32 v4, s13, v142
	s_waitcnt lgkmcnt(4)
	v_cvt_pk_bf16_f32 v31, v44, v46
	s_waitcnt lgkmcnt(2)
	v_cvt_pk_bf16_f32 v32, v48, v50
	s_waitcnt lgkmcnt(0)
	v_cvt_pk_bf16_f32 v33, v52, v54
	global_store_dwordx4 v[56:57], v[30:33], off
	s_waitcnt vmcnt(0)
	v_mov_b64_e32 v[98:99], v[118:119]
	v_mov_b64_e32 v[82:83], v[122:123]
	v_cvt_pk_bf16_f32 v30, v43, v5
	v_ashrrev_i32_e32 v5, 31, v4
	v_lshlrev_b64 v[4:5], 12, v[4:5]
	v_lshl_add_u64 v[4:5], s[2:3], 0, v[4:5]
	v_lshl_add_u64 v[4:5], v[4:5], 0, s[4:5]
	v_lshl_add_u64 v[4:5], v[4:5], 0, v[136:137]
	v_cvt_pk_bf16_f32 v31, v45, v47
	v_cvt_pk_bf16_f32 v32, v49, v51
	v_cvt_pk_bf16_f32 v33, v53, v55
	ds_read2_b32 v[42:43], v141 offset0:16 offset1:24
	ds_read2_b32 v[44:45], v141 offset0:81 offset1:89
	ds_read2_b32 v[46:47], v141 offset0:146 offset1:154
	ds_read2_b32 v[48:49], v141 offset0:211 offset1:219
	ds_read2_b32 v[50:51], v2 offset0:20 offset1:28
	ds_read2_b32 v[52:53], v2 offset0:85 offset1:93
	ds_read2_b32 v[54:55], v2 offset0:150 offset1:158
	ds_read2_b32 v[56:57], v2 offset0:215 offset1:223
	global_store_dwordx4 v[4:5], v[30:33], off
	v_add_u32_e32 v4, s13, v143
	v_ashrrev_i32_e32 v5, 31, v4
	v_lshlrev_b64 v[4:5], 12, v[4:5]
	v_lshl_add_u64 v[4:5], s[2:3], 0, v[4:5]
	v_lshl_add_u64 v[4:5], v[4:5], 0, s[4:5]
	v_lshl_add_u64 v[4:5], v[4:5], 0, v[136:137]
	s_waitcnt lgkmcnt(6)
	v_cvt_pk_bf16_f32 v30, v42, v44
	s_waitcnt lgkmcnt(4)
	v_cvt_pk_bf16_f32 v31, v46, v48
	s_waitcnt lgkmcnt(2)
	v_cvt_pk_bf16_f32 v32, v50, v52
	s_waitcnt lgkmcnt(0)
; #define LAS __attribute__((address_space(3)))
; __device__ __forceinline__ unsigned pk2(float lo, float hi) { return cvtpk(lo, hi); }
; __device__ __forceinline__ void tr_finish(const TrItem& t, const f32x4 (&v)[16], LAS float* scr, int lane) {
;     ...
;     for (int j = 0; j < 8; ++j) { const int n = (lane >> 3) + 8 * j; const LAS float* s = scr + (8 * c) * 65 + n;
;         v4u o; o.x = pk2(s[0 * 65], s[1 * 65]); o.y = pk2(s[2 * 65], s[3 * 65]); o.z = pk2(s[4 * 65], s[5 * 65]); o.w = pk2(s[6 * 65], s[7 * 65]);
;         if (t.n0 + n < t.N) *(v4u*)(t.WT + (size_t)(t.drow0 + n) * t.K + t.k0 + 8 * c) = o; }
;     ...
;     for (; it < it1; it += NGW) {
;         const bool more = it + NGW < it1;
;         if (more) { TR_DESCRIBE(it + NGW, tn); tr_load(tn, vn, lane); }
;         tr_finish(tc, vc, scr, lane);
;         if (more) { tc = tn;
; #pragma unroll
;             for (int i = 0; i < 16; ++i) vc[i] = vn[i]; }
	v_cvt_pk_bf16_f32 v33, v54, v56
	global_store_dwordx4 v[4:5], v[30:33], off
	v_add_u32_e32 v4, s13, v144
	v_ashrrev_i32_e32 v5, 31, v4
	v_lshlrev_b64 v[4:5], 12, v[4:5]
	v_lshl_add_u64 v[4:5], s[2:3], 0, v[4:5]
	v_lshl_add_u64 v[4:5], v[4:5], 0, s[4:5]
	v_lshl_add_u64 v[4:5], v[4:5], 0, v[136:137]
	v_cvt_pk_bf16_f32 v30, v43, v45
	v_cvt_pk_bf16_f32 v31, v47, v49
	v_cvt_pk_bf16_f32 v32, v51, v53
	v_cvt_pk_bf16_f32 v33, v55, v57
	ds_read2_b32 v[42:43], v141 offset0:32 offset1:40
	ds_read2_b32 v[44:45], v141 offset0:97 offset1:105
	ds_read2_b32 v[46:47], v141 offset0:162 offset1:170
	ds_read2_b32 v[48:49], v141 offset0:227 offset1:235
	ds_read2_b32 v[50:51], v2 offset0:36 offset1:44
	ds_read2_b32 v[52:53], v2 offset0:101 offset1:109
	ds_read2_b32 v[54:55], v2 offset0:166 offset1:174
	ds_read2_b32 v[56:57], v2 offset0:231 offset1:239
	global_store_dwordx4 v[4:5], v[30:33], off
	v_add_u32_e32 v4, s13, v145
	v_ashrrev_i32_e32 v5, 31, v4
	v_lshlrev_b64 v[4:5], 12, v[4:5]
	v_lshl_add_u64 v[4:5], s[2:3], 0, v[4:5]
	v_lshl_add_u64 v[4:5], v[4:5], 0, s[4:5]
	v_lshl_add_u64 v[4:5], v[4:5], 0, v[136:137]
	s_waitcnt lgkmcnt(6)
	v_cvt_pk_bf16_f32 v30, v42, v44
	s_waitcnt lgkmcnt(4)
	v_cvt_pk_bf16_f32 v31, v46, v48
	s_waitcnt lgkmcnt(2)
	v_cvt_pk_bf16_f32 v32, v50, v52
	s_waitcnt lgkmcnt(0)
	v_cvt_pk_bf16_f32 v33, v54, v56
	global_store_dwordx4 v[4:5], v[30:33], off
	v_add_u32_e32 v4, s13, v146
	v_ashrrev_i32_e32 v5, 31, v4
	v_lshlrev_b64 v[4:5], 12, v[4:5]
	v_lshl_add_u64 v[4:5], s[2:3], 0, v[4:5]
	v_lshl_add_u64 v[4:5], v[4:5], 0, s[4:5]
	v_lshl_add_u64 v[4:5], v[4:5], 0, v[136:137]
	v_cvt_pk_bf16_f32 v30, v43, v45
	v_cvt_pk_bf16_f32 v31, v47, v49
	v_cvt_pk_bf16_f32 v32, v51, v53
	v_cvt_pk_bf16_f32 v33, v55, v57
	ds_read2_b32 v[42:43], v141 offset0:48 offset1:56
	ds_read2_b32 v[44:45], v141 offset0:113 offset1:121
	ds_read2_b32 v[46:47], v141 offset0:178 offset1:186
	ds_read2_b32 v[48:49], v141 offset0:243 offset1:251
	ds_read2_b32 v[50:51], v2 offset0:52 offset1:60
	ds_read2_b32 v[52:53], v2 offset0:117 offset1:125
	ds_read2_b32 v[54:55], v2 offset0:182 offset1:190
	ds_read2_b32 v[56:57], v2 offset0:247 offset1:255
	global_store_dwordx4 v[4:5], v[30:33], off
	v_add_u32_e32 v4, s13, v147
	v_ashrrev_i32_e32 v5, 31, v4
	v_lshlrev_b64 v[4:5], 12, v[4:5]
	v_lshl_add_u64 v[4:5], s[2:3], 0, v[4:5]
	v_lshl_add_u64 v[4:5], v[4:5], 0, s[4:5]
	v_lshl_add_u64 v[4:5], v[4:5], 0, v[136:137]
	s_waitcnt lgkmcnt(6)
	v_cvt_pk_bf16_f32 v30, v42, v44
	s_waitcnt lgkmcnt(4)
	v_cvt_pk_bf16_f32 v31, v46, v48
	s_waitcnt lgkmcnt(2)
	v_cvt_pk_bf16_f32 v32, v50, v52
	s_waitcnt lgkmcnt(0)
	v_cvt_pk_bf16_f32 v33, v54, v56
	global_store_dwordx4 v[4:5], v[30:33], off
	v_add_u32_e32 v4, s13, v148
	v_ashrrev_i32_e32 v5, 31, v4
	v_lshlrev_b64 v[4:5], 12, v[4:5]
	v_lshl_add_u64 v[4:5], s[2:3], 0, v[4:5]
	v_lshl_add_u64 v[4:5], v[4:5], 0, s[4:5]
	v_lshl_add_u64 v[4:5], v[4:5], 0, v[136:137]
	v_cvt_pk_bf16_f32 v30, v43, v45
	v_cvt_pk_bf16_f32 v31, v47, v49
	v_cvt_pk_bf16_f32 v32, v51, v53
	v_cvt_pk_bf16_f32 v33, v55, v57
	global_store_dwordx4 v[4:5], v[30:33], off
	s_waitcnt lgkmcnt(0)
	v_mov_b64_e32 v[86:87], v[102:103]
	v_mov_b64_e32 v[74:75], v[106:107]
	v_mov_b64_e32 v[78:79], v[90:91]
	v_mov_b64_e32 v[66:67], v[94:95]
	v_mov_b64_e32 v[72:73], v[36:37]
	v_mov_b64_e32 v[60:61], v[40:41]
	v_mov_b64_e32 v[64:65], v[24:25]
	v_mov_b64_e32 v[52:53], v[28:29]
	v_mov_b64_e32 v[56:57], v[8:9]
	v_mov_b64_e32 v[44:45], v[20:21]
	v_mov_b64_e32 v[48:49], v[12:13]
	v_mov_b64_e32 v[32:33], v[16:17]
	s_add_i32 s14, s14, s15
	s_andn2_b64 vcc, exec, s[6:7]
	v_mov_b64_e32 v[100:101], v[120:121]
	v_mov_b64_e32 v[84:85], v[124:125]
	v_mov_b64_e32 v[88:89], v[104:105]
	v_mov_b64_e32 v[76:77], v[108:109]
	v_mov_b64_e32 v[80:81], v[92:93]
	v_mov_b64_e32 v[68:69], v[96:97]
	v_mov_b64_e32 v[70:71], v[34:35]
	v_mov_b64_e32 v[58:59], v[38:39]
	v_mov_b64_e32 v[62:63], v[22:23]
	v_mov_b64_e32 v[50:51], v[26:27]
	v_mov_b64_e32 v[54:55], v[6:7]
	v_mov_b64_e32 v[42:43], v[18:19]
	v_mov_b64_e32 v[46:47], v[10:11]
	v_mov_b64_e32 v[30:31], v[14:15]
	s_mov_b32 s13, s8
	s_mov_b32 s4, s16
	v_mov_b32_e32 v114, v130
	v_mov_b32_e32 v115, v131
	v_mov_b32_e32 v116, v132
	v_mov_b32_e32 v117, v133
	v_mov_b32_e32 v110, v126
	v_mov_b32_e32 v111, v127
	v_mov_b32_e32 v112, v128
	v_mov_b32_e32 v113, v129
	s_cbranch_vccz .LBB0_1210
.LBB0_1193:
	s_waitcnt vmcnt(0)
	v_readlane_b32 s5, v252, 62
	s_add_i32 s12, s5, s12
	s_cmpk_gt_i32 s12, 0x15ff
	s_cselect_b64 s[6:7], -1, 0
	s_and_b64 vcc, exec, s[6:7]
	s_cbranch_vccnz .LBB0_1192
	s_mul_hi_i32 s5, s12, 0x2e8ba2e9
	s_lshr_b32 s8, s5, 31
	s_ashr_i32 s17, s5, 5
	s_add_i32 s17, s17, s8
	s_mul_i32 s5, s17, 0xffffd400
	s_add_i32 s8, s14, s5
	v_mov_b32_e32 v8, v3
	v_mov_b32_e32 v9, v3
	s_lshl_b32 s16, s17, 6
	v_add_u32_e32 v2, s8, v134
	s_movk_i32 s9, 0x2c00
	v_mov_b32_e32 v6, v3
	v_mov_b32_e32 v7, v3
	v_mov_b64_e32 v[12:13], v[8:9]
	v_mov_b64_e32 v[16:17], v[8:9]
	v_cmp_gt_i32_e32 vcc, s9, v2
	v_or_b32_e32 v137, s16, v135
	v_lshlrev_b32_e32 v138, 2, v134
	v_mov_b64_e32 v[10:11], v[6:7]
	v_mov_b64_e32 v[14:15], v[6:7]
	s_and_saveexec_b64 s[10:11], vcc
	s_mov_b32 s24, 0xb000
	s_cbranch_execz .LBB0_1196
	v_mov_b64_e32 v[4:5], s[0:1]
	v_mad_i64_i32 v[10:11], s[20:21], v137, s24, v[4:5]
	s_ashr_i32 s9, s8, 31
	s_lshl_b64 s[20:21], s[8:9], 2
	v_or_b32_e32 v2, 4, v137
	v_lshl_add_u64 v[10:11], v[10:11], 0, s[20:21]
	v_mov_b32_e32 v139, v3
	v_mad_i64_i32 v[4:5], s[22:23], v2, s24, v[4:5]
	v_lshl_add_u64 v[10:11], v[10:11], 0, v[138:139]
	v_lshl_add_u64 v[4:5], v[4:5], 0, s[20:21]
	v_lshl_add_u64 v[4:5], v[4:5], 0, v[138:139]
	global_load_dwordx4 v[14:17], v[10:11], off
	s_nop 0
	global_load_dwordx4 v[10:13], v[4:5], off
